# phase 10: the next tile's rstd reduction moved from behind the last store into the middle of the SwiGLU epilogue body (its two LDS round trips overlap the other wave's work); results parked in tempora
# speedup vs baseline: 1.0013x; 1.0013x over previous
.LBB0_1093:
	ds_read_b128 v[146:149], v167
	ds_read_b128 v[150:153], v167 offset:1024
	ds_read_b128 v[178:181], v167 offset:2048
	ds_read_b128 v[182:185], v167 offset:3072
	s_add_u32 s28, s0, 0xfffc0080
	s_addc_u32 s29, s1, -1
	s_cmp_eq_u32 s64, 12
	s_cselect_b32 s45, s37, s29
	s_cselect_b32 s44, s60, s28
	s_cselect_b32 s43, s13, s63
	s_cselect_b32 s42, s61, s62
	v_lshl_add_u64 v[156:157], s[0:1], 0, v[138:139]
	s_add_i32 m0, s47, 0xc000
	ds_read_b128 v[186:189], v171
	ds_read_b128 v[196:199], v171 offset:1024
	ds_read_b128 v[200:203], v171 offset:2048
	ds_read_b128 v[204:207], v171 offset:3072
	ds_read_b128 v[208:211], v171 offset:4096
	ds_read_b128 v[212:215], v171 offset:5120
	ds_read_b128 v[216:219], v171 offset:6144
	ds_read_b128 v[220:223], v171 offset:7168
	global_load_lds_dwordx4 v[156:157], off
	v_lshl_add_u64 v[156:157], s[0:1], 0, v[140:141]
	s_add_i32 m0, s47, 0xe000
	s_nop 0
	global_load_lds_dwordx4 v[156:157], off
	s_waitcnt lgkmcnt(8)
	s_barrier
	s_waitcnt lgkmcnt(0)
	v_mfma_f32_16x16x32_bf16 v[124:127], v[146:149], v[186:189], v[124:127]
	v_mfma_f32_16x16x32_bf16 v[120:123], v[178:181], v[186:189], v[120:123]
	v_mfma_f32_16x16x32_bf16 v[108:111], v[146:149], v[200:203], v[108:111]
	v_mfma_f32_16x16x32_bf16 v[104:107], v[178:181], v[200:203], v[104:107]
	v_mfma_f32_16x16x32_bf16 v[92:95], v[146:149], v[208:211], v[92:95]
	v_mfma_f32_16x16x32_bf16 v[88:91], v[178:181], v[208:211], v[88:91]
	v_mfma_f32_16x16x32_bf16 v[76:79], v[146:149], v[216:219], v[76:79]
	v_mfma_f32_16x16x32_bf16 v[72:75], v[178:181], v[216:219], v[72:75]
	v_mfma_f32_16x16x32_bf16 v[124:127], v[150:153], v[196:199], v[124:127]
	v_mfma_f32_16x16x32_bf16 v[120:123], v[182:185], v[196:199], v[120:123]
	v_mfma_f32_16x16x32_bf16 v[108:111], v[150:153], v[204:207], v[108:111]
	v_mfma_f32_16x16x32_bf16 v[104:107], v[182:185], v[204:207], v[104:107]
	v_mfma_f32_16x16x32_bf16 v[92:95], v[150:153], v[212:215], v[92:95]
	v_mfma_f32_16x16x32_bf16 v[88:91], v[182:185], v[212:215], v[88:91]
	v_mfma_f32_16x16x32_bf16 v[76:79], v[150:153], v[220:223], v[76:79]
	v_mfma_f32_16x16x32_bf16 v[72:75], v[182:185], v[220:223], v[72:75]
	s_barrier
	s_add_i32 s28, s56, s11
	v_lshl_add_u64 v[156:157], s[42:43], 0, v[132:133]
	s_mov_b32 m0, s28
	ds_read_b128 v[224:227], v175
	ds_read_b128 v[228:231], v175 offset:1024
	ds_read_b128 v[232:235], v175 offset:2048
	ds_read_b128 v[236:239], v175 offset:3072
	global_load_lds_dwordx4 v[156:157], off
	v_lshl_add_u64 v[160:161], s[42:43], 0, v[128:129]
	s_add_i32 m0, s28, 0x2000
	s_nop 0
	global_load_lds_dwordx4 v[160:161], off
	s_barrier
	s_waitcnt lgkmcnt(0)
	v_mfma_f32_16x16x32_bf16 v[116:119], v[224:227], v[186:189], v[116:119]
	v_mfma_f32_16x16x32_bf16 v[112:115], v[232:235], v[186:189], v[112:115]
	v_mfma_f32_16x16x32_bf16 v[100:103], v[224:227], v[200:203], v[100:103]
	v_mfma_f32_16x16x32_bf16 v[96:99], v[232:235], v[200:203], v[96:99]
	v_mfma_f32_16x16x32_bf16 v[84:87], v[224:227], v[208:211], v[84:87]
	v_mfma_f32_16x16x32_bf16 v[80:83], v[232:235], v[208:211], v[80:83]
	v_mfma_f32_16x16x32_bf16 v[68:71], v[224:227], v[216:219], v[68:71]
	v_mfma_f32_16x16x32_bf16 v[64:67], v[232:235], v[216:219], v[64:67]
	v_mfma_f32_16x16x32_bf16 v[116:119], v[228:231], v[196:199], v[116:119]
	v_mfma_f32_16x16x32_bf16 v[112:115], v[236:239], v[196:199], v[112:115]
	v_mfma_f32_16x16x32_bf16 v[100:103], v[228:231], v[204:207], v[100:103]
	v_mfma_f32_16x16x32_bf16 v[96:99], v[236:239], v[204:207], v[96:99]
	v_mfma_f32_16x16x32_bf16 v[84:87], v[228:231], v[212:215], v[84:87]
	v_mfma_f32_16x16x32_bf16 v[80:83], v[236:239], v[212:215], v[80:83]
	v_mfma_f32_16x16x32_bf16 v[68:71], v[228:231], v[220:223], v[68:71]
	v_mfma_f32_16x16x32_bf16 v[64:67], v[236:239], v[220:223], v[64:67]
	s_mov_b32 m0, s47
	v_lshl_add_u64 v[164:165], s[44:45], 0, v[134:135]
	s_barrier
	ds_read_b128 v[186:189], v171 offset:16384
	ds_read_b128 v[196:199], v171 offset:17408
	ds_read_b128 v[200:203], v171 offset:18432
	ds_read_b128 v[204:207], v171 offset:19456
	ds_read_b128 v[208:211], v171 offset:20480
	ds_read_b128 v[212:215], v171 offset:21504
	ds_read_b128 v[216:219], v171 offset:22528
	ds_read_b128 v[220:223], v171 offset:23552
	global_load_lds_dwordx4 v[164:165], off
	v_lshl_add_u64 v[168:169], s[44:45], 0, v[130:131]
	s_mov_b32 m0, s48
	s_nop 0
	global_load_lds_dwordx4 v[168:169], off
	s_barrier
	s_waitcnt lgkmcnt(0)
	v_mfma_f32_16x16x32_bf16 v[60:63], v[146:149], v[186:189], v[60:63]
	v_mfma_f32_16x16x32_bf16 v[56:59], v[178:181], v[186:189], v[56:59]
	v_mfma_f32_16x16x32_bf16 v[44:47], v[146:149], v[200:203], v[44:47]
	v_mfma_f32_16x16x32_bf16 v[40:43], v[178:181], v[200:203], v[40:43]
	v_mfma_f32_16x16x32_bf16 v[28:31], v[146:149], v[208:211], v[28:31]
	v_mfma_f32_16x16x32_bf16 v[24:27], v[178:181], v[208:211], v[24:27]
	v_mfma_f32_16x16x32_bf16 v[12:15], v[146:149], v[216:219], v[12:15]
	v_mfma_f32_16x16x32_bf16 v[8:11], v[178:181], v[216:219], v[8:11]
	v_mfma_f32_16x16x32_bf16 v[60:63], v[150:153], v[196:199], v[60:63]
	v_mfma_f32_16x16x32_bf16 v[56:59], v[182:185], v[196:199], v[56:59]
	v_mfma_f32_16x16x32_bf16 v[44:47], v[150:153], v[204:207], v[44:47]
	v_mfma_f32_16x16x32_bf16 v[40:43], v[182:185], v[204:207], v[40:43]
	v_mfma_f32_16x16x32_bf16 v[28:31], v[150:153], v[212:215], v[28:31]
	v_mfma_f32_16x16x32_bf16 v[24:27], v[182:185], v[212:215], v[24:27]
	v_mfma_f32_16x16x32_bf16 v[12:15], v[150:153], v[220:223], v[12:15]
	v_mfma_f32_16x16x32_bf16 v[8:11], v[182:185], v[220:223], v[8:11]
	s_barrier
	s_add_u32 s66, s42, 0x40000
	s_addc_u32 s67, s43, 0
	s_add_i32 s28, s57, s11
	v_lshl_add_u64 v[146:147], s[66:67], 0, v[132:133]
	s_mov_b32 m0, s28
	s_nop 0
	global_load_lds_dwordx4 v[146:147], off
	v_lshl_add_u64 v[146:147], s[66:67], 0, v[128:129]
	s_add_i32 m0, s28, 0x2000
	s_nop 0
	global_load_lds_dwordx4 v[146:147], off
	s_waitcnt vmcnt(6)
	s_barrier
	v_mfma_f32_16x16x32_bf16 v[52:55], v[224:227], v[186:189], v[52:55]
	v_mfma_f32_16x16x32_bf16 v[48:51], v[232:235], v[186:189], v[48:51]
	v_mfma_f32_16x16x32_bf16 v[36:39], v[224:227], v[200:203], v[36:39]
	v_mfma_f32_16x16x32_bf16 v[32:35], v[232:235], v[200:203], v[32:35]
	v_mfma_f32_16x16x32_bf16 v[20:23], v[224:227], v[208:211], v[20:23]
	v_mfma_f32_16x16x32_bf16 v[16:19], v[232:235], v[208:211], v[16:19]
	v_mfma_f32_16x16x32_bf16 v[4:7], v[224:227], v[216:219], v[4:7]
	v_mfma_f32_16x16x32_bf16 v[0:3], v[232:235], v[216:219], v[0:3]
	v_mfma_f32_16x16x32_bf16 v[52:55], v[228:231], v[196:199], v[52:55]
	v_mfma_f32_16x16x32_bf16 v[48:51], v[236:239], v[196:199], v[48:51]
	v_mfma_f32_16x16x32_bf16 v[36:39], v[228:231], v[204:207], v[36:39]
	v_mfma_f32_16x16x32_bf16 v[32:35], v[236:239], v[204:207], v[32:35]
	v_mfma_f32_16x16x32_bf16 v[20:23], v[228:231], v[212:215], v[20:23]
	v_mfma_f32_16x16x32_bf16 v[16:19], v[236:239], v[212:215], v[16:19]
	v_mfma_f32_16x16x32_bf16 v[4:7], v[228:231], v[220:223], v[4:7]
	v_mfma_f32_16x16x32_bf16 v[0:3], v[236:239], v[220:223], v[0:3]
	s_add_i32 s28, 0, 0x18000
	v_add_u32_e32 v154, s28, v159
	s_barrier
	ds_read_b128 v[146:149], v154
	ds_read_b128 v[150:153], v154 offset:1024
	ds_read_b128 v[178:181], v154 offset:2048
	ds_read_b128 v[182:185], v154 offset:3072
	s_add_u32 s44, s44, 0x40000
	s_addc_u32 s45, s45, 0
	s_mov_b32 m0, s49
	v_lshl_add_u64 v[172:173], s[44:45], 0, v[134:135]
	ds_read_b128 v[186:189], v171 offset:32768
	ds_read_b128 v[196:199], v171 offset:33792
	ds_read_b128 v[200:203], v171 offset:34816
	ds_read_b128 v[204:207], v171 offset:35840
	ds_read_b128 v[208:211], v171 offset:36864
	ds_read_b128 v[212:215], v171 offset:37888
	ds_read_b128 v[216:219], v171 offset:38912
	ds_read_b128 v[220:223], v171 offset:39936
	global_load_lds_dwordx4 v[172:173], off
	v_lshl_add_u64 v[172:173], s[44:45], 0, v[130:131]
	s_mov_b32 m0, s50
	s_nop 0
	global_load_lds_dwordx4 v[172:173], off
	s_waitcnt lgkmcnt(8)
	s_barrier
	s_waitcnt lgkmcnt(0)
	v_mfma_f32_16x16x32_bf16 v[124:127], v[146:149], v[186:189], v[124:127]
	v_mfma_f32_16x16x32_bf16 v[120:123], v[178:181], v[186:189], v[120:123]
	v_mfma_f32_16x16x32_bf16 v[108:111], v[146:149], v[200:203], v[108:111]
	v_mfma_f32_16x16x32_bf16 v[104:107], v[178:181], v[200:203], v[104:107]
	v_mfma_f32_16x16x32_bf16 v[92:95], v[146:149], v[208:211], v[92:95]
	v_mfma_f32_16x16x32_bf16 v[88:91], v[178:181], v[208:211], v[88:91]
	v_mfma_f32_16x16x32_bf16 v[76:79], v[146:149], v[216:219], v[76:79]
	v_mfma_f32_16x16x32_bf16 v[72:75], v[178:181], v[216:219], v[72:75]
	v_mfma_f32_16x16x32_bf16 v[124:127], v[150:153], v[196:199], v[124:127]
	v_mfma_f32_16x16x32_bf16 v[120:123], v[182:185], v[196:199], v[120:123]
	v_mfma_f32_16x16x32_bf16 v[108:111], v[150:153], v[204:207], v[108:111]
	v_mfma_f32_16x16x32_bf16 v[104:107], v[182:185], v[204:207], v[104:107]
	v_mfma_f32_16x16x32_bf16 v[92:95], v[150:153], v[212:215], v[92:95]
	v_mfma_f32_16x16x32_bf16 v[88:91], v[182:185], v[212:215], v[88:91]
	v_mfma_f32_16x16x32_bf16 v[76:79], v[150:153], v[220:223], v[76:79]
	v_mfma_f32_16x16x32_bf16 v[72:75], v[182:185], v[220:223], v[72:75]
	s_barrier
	s_add_i32 s29, 0, 0x1c000
	s_add_i32 s28, s28, s11
	v_add_u32_e32 v154, s29, v159
	v_lshl_add_u64 v[156:157], v[156:157], 0, s[6:7]
	s_mov_b32 m0, s28
	ds_read_b128 v[224:227], v154
	ds_read_b128 v[228:231], v154 offset:1024
	ds_read_b128 v[232:235], v154 offset:2048
	ds_read_b128 v[236:239], v154 offset:3072
	global_load_lds_dwordx4 v[156:157], off
	v_lshl_add_u64 v[156:157], v[160:161], 0, s[6:7]
	s_add_i32 m0, s28, 0x2000
	s_nop 0
	global_load_lds_dwordx4 v[156:157], off
	s_barrier
	s_waitcnt lgkmcnt(0)
	v_mfma_f32_16x16x32_bf16 v[116:119], v[224:227], v[186:189], v[116:119]
	v_mfma_f32_16x16x32_bf16 v[112:115], v[232:235], v[186:189], v[112:115]
	v_mfma_f32_16x16x32_bf16 v[100:103], v[224:227], v[200:203], v[100:103]
	v_mfma_f32_16x16x32_bf16 v[96:99], v[232:235], v[200:203], v[96:99]
	v_mfma_f32_16x16x32_bf16 v[84:87], v[224:227], v[208:211], v[84:87]
	v_mfma_f32_16x16x32_bf16 v[80:83], v[232:235], v[208:211], v[80:83]
	v_mfma_f32_16x16x32_bf16 v[68:71], v[224:227], v[216:219], v[68:71]
	v_mfma_f32_16x16x32_bf16 v[64:67], v[232:235], v[216:219], v[64:67]
	v_mfma_f32_16x16x32_bf16 v[116:119], v[228:231], v[196:199], v[116:119]
	v_mfma_f32_16x16x32_bf16 v[112:115], v[236:239], v[196:199], v[112:115]
	v_mfma_f32_16x16x32_bf16 v[100:103], v[228:231], v[204:207], v[100:103]
	v_mfma_f32_16x16x32_bf16 v[96:99], v[236:239], v[204:207], v[96:99]
	v_mfma_f32_16x16x32_bf16 v[84:87], v[228:231], v[212:215], v[84:87]
	v_mfma_f32_16x16x32_bf16 v[80:83], v[236:239], v[212:215], v[80:83]
	v_mfma_f32_16x16x32_bf16 v[68:71], v[228:231], v[220:223], v[68:71]
	v_mfma_f32_16x16x32_bf16 v[64:67], v[236:239], v[220:223], v[64:67]
	s_mov_b32 m0, s53
	v_lshl_add_u64 v[156:157], v[164:165], 0, s[6:7]
	s_barrier
	ds_read_b128 v[186:189], v171 offset:49152
	ds_read_b128 v[196:199], v171 offset:50176
	ds_read_b128 v[200:203], v171 offset:51200
	ds_read_b128 v[204:207], v171 offset:52224
	ds_read_b128 v[208:211], v171 offset:53248
	ds_read_b128 v[212:215], v171 offset:54272
	ds_read_b128 v[216:219], v171 offset:55296
	ds_read_b128 v[220:223], v171 offset:56320
	global_load_lds_dwordx4 v[156:157], off
	v_lshl_add_u64 v[156:157], v[168:169], 0, s[6:7]
	s_mov_b32 m0, s54
	s_nop 0
	global_load_lds_dwordx4 v[156:157], off
	s_barrier
	s_waitcnt lgkmcnt(0)
	v_mfma_f32_16x16x32_bf16 v[60:63], v[146:149], v[186:189], v[60:63]
	v_mfma_f32_16x16x32_bf16 v[56:59], v[178:181], v[186:189], v[56:59]
	v_mfma_f32_16x16x32_bf16 v[44:47], v[146:149], v[200:203], v[44:47]
	v_mfma_f32_16x16x32_bf16 v[40:43], v[178:181], v[200:203], v[40:43]
	v_mfma_f32_16x16x32_bf16 v[28:31], v[146:149], v[208:211], v[28:31]
	v_mfma_f32_16x16x32_bf16 v[24:27], v[178:181], v[208:211], v[24:27]
	v_mfma_f32_16x16x32_bf16 v[12:15], v[146:149], v[216:219], v[12:15]
	v_mfma_f32_16x16x32_bf16 v[8:11], v[178:181], v[216:219], v[8:11]
	v_mfma_f32_16x16x32_bf16 v[60:63], v[150:153], v[196:199], v[60:63]
	v_mfma_f32_16x16x32_bf16 v[56:59], v[182:185], v[196:199], v[56:59]
	v_mfma_f32_16x16x32_bf16 v[44:47], v[150:153], v[204:207], v[44:47]
	v_mfma_f32_16x16x32_bf16 v[40:43], v[182:185], v[204:207], v[40:43]
	v_mfma_f32_16x16x32_bf16 v[28:31], v[150:153], v[212:215], v[28:31]
	v_mfma_f32_16x16x32_bf16 v[24:27], v[182:185], v[212:215], v[24:27]
	v_mfma_f32_16x16x32_bf16 v[12:15], v[150:153], v[220:223], v[12:15]
	v_mfma_f32_16x16x32_bf16 v[8:11], v[182:185], v[220:223], v[8:11]
	s_barrier
	s_add_u32 s42, s42, 0x40080
	s_addc_u32 s43, s43, 0
	s_add_i32 s28, s29, s11
	v_lshl_add_u64 v[146:147], s[42:43], 0, v[132:133]
	s_mov_b32 m0, s28
	s_nop 0
	global_load_lds_dwordx4 v[146:147], off
	v_lshl_add_u64 v[146:147], s[42:43], 0, v[128:129]
	s_add_i32 m0, s28, 0x2000
	s_nop 0
	global_load_lds_dwordx4 v[146:147], off
	s_waitcnt vmcnt(6)
	s_barrier
	v_mfma_f32_16x16x32_bf16 v[52:55], v[224:227], v[186:189], v[52:55]
	v_mfma_f32_16x16x32_bf16 v[48:51], v[232:235], v[186:189], v[48:51]
	v_mfma_f32_16x16x32_bf16 v[36:39], v[224:227], v[200:203], v[36:39]
	v_mfma_f32_16x16x32_bf16 v[32:35], v[232:235], v[200:203], v[32:35]
	v_mfma_f32_16x16x32_bf16 v[20:23], v[224:227], v[208:211], v[20:23]
	v_mfma_f32_16x16x32_bf16 v[16:19], v[232:235], v[208:211], v[16:19]
	v_mfma_f32_16x16x32_bf16 v[4:7], v[224:227], v[216:219], v[4:7]
	v_mfma_f32_16x16x32_bf16 v[0:3], v[232:235], v[216:219], v[0:3]
	v_mfma_f32_16x16x32_bf16 v[52:55], v[228:231], v[196:199], v[52:55]
	v_mfma_f32_16x16x32_bf16 v[48:51], v[236:239], v[196:199], v[48:51]
	v_mfma_f32_16x16x32_bf16 v[36:39], v[228:231], v[204:207], v[36:39]
	v_mfma_f32_16x16x32_bf16 v[32:35], v[236:239], v[204:207], v[32:35]
	v_mfma_f32_16x16x32_bf16 v[20:23], v[228:231], v[212:215], v[20:23]
	v_mfma_f32_16x16x32_bf16 v[16:19], v[236:239], v[212:215], v[16:19]
	v_mfma_f32_16x16x32_bf16 v[4:7], v[228:231], v[220:223], v[4:7]
	v_mfma_f32_16x16x32_bf16 v[0:3], v[236:239], v[220:223], v[0:3]
	s_add_i32 s64, s64, 2
	s_add_u32 s0, s0, 0x100
	s_addc_u32 s1, s1, 0
	s_add_u32 s62, s62, 0x100
	s_addc_u32 s63, s63, 0
	s_cmp_gt_u32 s64, 13
	s_barrier
	s_cbranch_scc0 .LBB0_1093
	v_lshl_add_u32 v168, s4, 8, v155
	v_or_b32_e32 v164, 16, v168
	v_or_b32_e32 v160, 32, v168
	v_or_b32_e32 v156, 48, v168
	v_add_u32_e32 v152, 0x80, v168
	v_add_u32_e32 v150, 0x90, v168
	v_add_u32_e32 v148, 0xa0, v168
	v_add_u32_e32 v146, 0xb0, v168
	v_lshl_or_b32 v172, s5, 7, v163
	v_mov_b32_e32 v178, v240
	v_mov_b32_e32 v179, v240
	v_mov_b32_e32 v154, v241
	s_and_b32 s0, s36, 0x7f
	v_lshl_add_u32 v228, s0, 8, v155
	v_mov_b32_e32 v229, 0
	v_lshlrev_b32_e32 v228, 6, v228
	v_lshl_add_u64 v[230:231], v[136:137], 0, v[228:229]
	v_mov_b32_e32 v228, 0x2000
	v_lshl_add_u64 v[232:233], v[230:231], 0, v[228:229]
	global_load_dwordx4 v[216:219], v[230:231], off
	global_load_dwordx4 v[220:223], v[230:231], off offset:1024
	global_load_dwordx4 v[224:227], v[230:231], off offset:2048
	global_load_dwordx4 v[196:199], v[230:231], off offset:3072
	global_load_dwordx4 v[200:203], v[232:233], off
	global_load_dwordx4 v[204:207], v[232:233], off offset:1024
	global_load_dwordx4 v[208:211], v[232:233], off offset:2048
	global_load_dwordx4 v[212:215], v[232:233], off offset:3072
	v_pk_mul_f32 v[124:125], v[124:125], v[178:179] op_sel_hi:[1,0]
	v_pk_mul_f32 v[126:127], v[126:127], v[178:179] op_sel_hi:[1,0]
	v_mul_f32_e32 v147, 0xbfb8aa3b, v124
	v_exp_f32_e32 v147, v147
	v_mul_f32_e32 v149, 0xbfb8aa3b, v125
	v_exp_f32_e32 v149, v149
	v_mul_f32_e32 v151, 0xbfb8aa3b, v127
	v_add_f32_e32 v147, 1.0, v147
	v_rcp_f32_e32 v180, v147
	v_add_f32_e32 v147, 1.0, v149
	v_mul_f32_e32 v149, 0xbfb8aa3b, v126
	v_exp_f32_e32 v149, v149
	v_exp_f32_e32 v151, v151
	v_rcp_f32_e32 v181, v147
	v_pk_mul_f32 v[116:117], v[116:117], v[178:179] op_sel_hi:[1,0]
	v_add_f32_e32 v147, 1.0, v149
	v_rcp_f32_e32 v182, v147
	v_add_f32_e32 v147, 1.0, v151
	v_rcp_f32_e32 v183, v147
	v_pk_mul_f32 v[124:125], v[124:125], v[180:181]
	v_pk_mul_f32 v[120:121], v[120:121], v[178:179] op_sel_hi:[1,0]
	v_pk_mul_f32 v[116:117], v[116:117], v[124:125]
	v_pk_mul_f32 v[124:125], v[126:127], v[182:183]
	v_mul_f32_e32 v126, 0xbfb8aa3b, v120
	v_exp_f32_e32 v126, v126
	v_pk_mul_f32 v[118:119], v[118:119], v[178:179] op_sel_hi:[1,0]
	v_pk_mul_f32 v[122:123], v[122:123], v[178:179] op_sel_hi:[1,0]
	v_pk_mul_f32 v[118:119], v[118:119], v[124:125]
	v_mul_f32_e32 v124, 0xbfb8aa3b, v121
	v_exp_f32_e32 v125, v124
	v_add_f32_e32 v124, 1.0, v126
	v_mul_f32_e32 v126, 0xbfb8aa3b, v122
	v_mul_f32_e32 v127, 0xbfb8aa3b, v123
	v_exp_f32_e32 v126, v126
	v_exp_f32_e32 v127, v127
	v_add_f32_e32 v125, 1.0, v125
	v_rcp_f32_e32 v124, v124
	v_rcp_f32_e32 v125, v125
	v_add_f32_e32 v126, 1.0, v126
	v_add_f32_e32 v127, 1.0, v127
	v_rcp_f32_e32 v126, v126
	v_rcp_f32_e32 v127, v127
	v_pk_mul_f32 v[112:113], v[112:113], v[178:179] op_sel_hi:[1,0]
	v_pk_mul_f32 v[120:121], v[120:121], v[124:125]
	v_pk_mul_f32 v[114:115], v[114:115], v[178:179] op_sel_hi:[1,0]
	v_pk_mul_f32 v[112:113], v[112:113], v[120:121]
	v_pk_mul_f32 v[120:121], v[122:123], v[126:127]
	v_ashrrev_i32_e32 v173, 31, v172
	v_pk_mul_f32 v[114:115], v[114:115], v[120:121]
	v_cvt_pk_bf16_f32 v116, v116, v117
	v_cvt_pk_bf16_f32 v117, v118, v119
	v_cvt_pk_bf16_f32 v118, v112, v113
	v_mov_b64_e32 v[112:113], s[20:21]
	v_cvt_pk_bf16_f32 v119, v114, v115
	v_mad_i64_i32 v[120:121], s[0:1], v168, s59, v[112:113]
	v_lshlrev_b64 v[114:115], 1, v[172:173]
	v_lshl_add_u64 v[120:121], v[120:121], 0, v[114:115]
	v_pk_mul_f32 v[108:109], v[108:109], v[176:177] op_sel_hi:[1,0]
	global_store_dwordx4 v[120:121], v[116:119], off
	v_mul_f32_e32 v122, 0xbfb8aa3b, v108
	v_pk_mul_f32 v[110:111], v[110:111], v[176:177] op_sel_hi:[1,0]
	v_mul_f32_e32 v116, 0xbfb8aa3b, v109
	v_exp_f32_e32 v122, v122
	v_exp_f32_e32 v117, v116
	v_mul_f32_e32 v118, 0xbfb8aa3b, v110
	v_mul_f32_e32 v119, 0xbfb8aa3b, v111
	v_exp_f32_e32 v118, v118
	v_exp_f32_e32 v119, v119
	v_add_f32_e32 v116, 1.0, v122
	v_add_f32_e32 v117, 1.0, v117
	v_rcp_f32_e32 v116, v116
	v_rcp_f32_e32 v117, v117
	v_add_f32_e32 v118, 1.0, v118
	v_add_f32_e32 v119, 1.0, v119
	v_rcp_f32_e32 v118, v118
	v_rcp_f32_e32 v119, v119
	v_pk_mul_f32 v[100:101], v[100:101], v[176:177] op_sel_hi:[1,0]
	v_pk_mul_f32 v[108:109], v[108:109], v[116:117]
	v_pk_mul_f32 v[104:105], v[104:105], v[176:177] op_sel_hi:[1,0]
	v_pk_mul_f32 v[100:101], v[100:101], v[108:109]
	v_pk_mul_f32 v[108:109], v[110:111], v[118:119]
	v_mul_f32_e32 v110, 0xbfb8aa3b, v104
	v_exp_f32_e32 v110, v110
	v_pk_mul_f32 v[102:103], v[102:103], v[176:177] op_sel_hi:[1,0]
	v_pk_mul_f32 v[106:107], v[106:107], v[176:177] op_sel_hi:[1,0]
	v_pk_mul_f32 v[102:103], v[102:103], v[108:109]
	v_mul_f32_e32 v108, 0xbfb8aa3b, v105
	v_exp_f32_e32 v109, v108
	v_add_f32_e32 v108, 1.0, v110
	v_mul_f32_e32 v110, 0xbfb8aa3b, v106
	v_mul_f32_e32 v111, 0xbfb8aa3b, v107
	v_exp_f32_e32 v110, v110
	v_exp_f32_e32 v111, v111
	v_add_f32_e32 v109, 1.0, v109
	v_rcp_f32_e32 v108, v108
	v_rcp_f32_e32 v109, v109
	v_add_f32_e32 v110, 1.0, v110
	v_add_f32_e32 v111, 1.0, v111
	v_rcp_f32_e32 v110, v110
	v_rcp_f32_e32 v111, v111
	v_pk_mul_f32 v[96:97], v[96:97], v[176:177] op_sel_hi:[1,0]
	v_pk_mul_f32 v[104:105], v[104:105], v[108:109]
	v_pk_mul_f32 v[92:93], v[92:93], v[174:175] op_sel_hi:[1,0]
	v_pk_mul_f32 v[104:105], v[96:97], v[104:105]
	v_pk_mul_f32 v[96:97], v[98:99], v[176:177] op_sel_hi:[1,0]
	v_pk_mul_f32 v[98:99], v[106:107], v[110:111]
	v_pk_mul_f32 v[94:95], v[94:95], v[174:175] op_sel_hi:[1,0]
	v_pk_mul_f32 v[106:107], v[96:97], v[98:99]
	v_cvt_pk_bf16_f32 v96, v100, v101
	v_mad_i64_i32 v[100:101], s[0:1], v164, s59, v[112:113]
	v_cvt_pk_bf16_f32 v97, v102, v103
	v_cvt_pk_bf16_f32 v98, v104, v105
	v_cvt_pk_bf16_f32 v99, v106, v107
	v_lshl_add_u64 v[100:101], v[100:101], 0, v[114:115]
	v_mul_f32_e32 v102, 0xbfb8aa3b, v92
	global_store_dwordx4 v[100:101], v[96:99], off
	v_exp_f32_e32 v102, v102
	v_pk_mul_f32 v[84:85], v[84:85], v[174:175] op_sel_hi:[1,0]
	v_mul_f32_e32 v96, 0xbfb8aa3b, v93
	v_exp_f32_e32 v97, v96
	v_mul_f32_e32 v98, 0xbfb8aa3b, v94
	v_mul_f32_e32 v99, 0xbfb8aa3b, v95
	v_exp_f32_e32 v98, v98
	v_exp_f32_e32 v99, v99
	v_add_f32_e32 v96, 1.0, v102
	v_add_f32_e32 v97, 1.0, v97
	v_rcp_f32_e32 v96, v96
	v_rcp_f32_e32 v97, v97
	v_add_f32_e32 v98, 1.0, v98
	v_add_f32_e32 v99, 1.0, v99
	v_rcp_f32_e32 v98, v98
	v_rcp_f32_e32 v99, v99
	v_pk_mul_f32 v[92:93], v[92:93], v[96:97]
	v_pk_mul_f32 v[88:89], v[88:89], v[174:175] op_sel_hi:[1,0]
	v_pk_mul_f32 v[84:85], v[84:85], v[92:93]
	v_pk_mul_f32 v[92:93], v[94:95], v[98:99]
	v_mul_f32_e32 v94, 0xbfb8aa3b, v88
	v_exp_f32_e32 v94, v94
	v_pk_mul_f32 v[86:87], v[86:87], v[174:175] op_sel_hi:[1,0]
	v_pk_mul_f32 v[90:91], v[90:91], v[174:175] op_sel_hi:[1,0]
	v_pk_mul_f32 v[86:87], v[86:87], v[92:93]
	v_mul_f32_e32 v92, 0xbfb8aa3b, v89
	v_exp_f32_e32 v93, v92
	v_add_f32_e32 v92, 1.0, v94
	v_mul_f32_e32 v94, 0xbfb8aa3b, v90
	v_mul_f32_e32 v95, 0xbfb8aa3b, v91
	v_exp_f32_e32 v94, v94
	v_exp_f32_e32 v95, v95
	v_add_f32_e32 v93, 1.0, v93
	v_rcp_f32_e32 v92, v92
	v_rcp_f32_e32 v93, v93
	v_add_f32_e32 v94, 1.0, v94
	v_add_f32_e32 v95, 1.0, v95
	v_rcp_f32_e32 v94, v94
	v_rcp_f32_e32 v95, v95
	v_pk_mul_f32 v[80:81], v[80:81], v[174:175] op_sel_hi:[1,0]
	v_pk_mul_f32 v[88:89], v[88:89], v[92:93]
	v_pk_mul_f32 v[76:77], v[76:77], v[170:171] op_sel_hi:[1,0]
	v_pk_mul_f32 v[88:89], v[80:81], v[88:89]
	v_pk_mul_f32 v[80:81], v[82:83], v[174:175] op_sel_hi:[1,0]
	v_pk_mul_f32 v[82:83], v[90:91], v[94:95]
	v_pk_mul_f32 v[78:79], v[78:79], v[170:171] op_sel_hi:[1,0]
	v_pk_mul_f32 v[90:91], v[80:81], v[82:83]
	v_cvt_pk_bf16_f32 v80, v84, v85
	v_mad_i64_i32 v[84:85], s[0:1], v160, s59, v[112:113]
	v_cvt_pk_bf16_f32 v81, v86, v87
	v_cvt_pk_bf16_f32 v82, v88, v89
	v_cvt_pk_bf16_f32 v83, v90, v91
	v_lshl_add_u64 v[84:85], v[84:85], 0, v[114:115]
	v_mul_f32_e32 v86, 0xbfb8aa3b, v76
	global_store_dwordx4 v[84:85], v[80:83], off
	v_exp_f32_e32 v86, v86
	v_pk_mul_f32 v[68:69], v[68:69], v[170:171] op_sel_hi:[1,0]
	v_mul_f32_e32 v80, 0xbfb8aa3b, v77
	v_exp_f32_e32 v81, v80
	v_mul_f32_e32 v82, 0xbfb8aa3b, v78
	v_mul_f32_e32 v83, 0xbfb8aa3b, v79
	v_exp_f32_e32 v82, v82
	v_exp_f32_e32 v83, v83
	v_add_f32_e32 v80, 1.0, v86
	v_add_f32_e32 v81, 1.0, v81
	v_rcp_f32_e32 v80, v80
	v_rcp_f32_e32 v81, v81
	v_add_f32_e32 v82, 1.0, v82
	v_add_f32_e32 v83, 1.0, v83
	v_rcp_f32_e32 v82, v82
	v_rcp_f32_e32 v83, v83
	v_pk_mul_f32 v[76:77], v[76:77], v[80:81]
	v_pk_mul_f32 v[72:73], v[72:73], v[170:171] op_sel_hi:[1,0]
	v_pk_mul_f32 v[68:69], v[68:69], v[76:77]
	v_pk_mul_f32 v[76:77], v[78:79], v[82:83]
	v_mul_f32_e32 v78, 0xbfb8aa3b, v72
	v_exp_f32_e32 v78, v78
	v_pk_mul_f32 v[70:71], v[70:71], v[170:171] op_sel_hi:[1,0]
	v_pk_mul_f32 v[74:75], v[74:75], v[170:171] op_sel_hi:[1,0]
	v_pk_mul_f32 v[70:71], v[70:71], v[76:77]
	v_mul_f32_e32 v76, 0xbfb8aa3b, v73
	v_exp_f32_e32 v77, v76
	v_add_f32_e32 v76, 1.0, v78
	v_mul_f32_e32 v78, 0xbfb8aa3b, v74
	v_mul_f32_e32 v79, 0xbfb8aa3b, v75
	v_exp_f32_e32 v78, v78
	v_exp_f32_e32 v79, v79
	v_add_f32_e32 v77, 1.0, v77
	v_rcp_f32_e32 v76, v76
	v_rcp_f32_e32 v77, v77
	v_add_f32_e32 v78, 1.0, v78
	v_add_f32_e32 v79, 1.0, v79
	v_rcp_f32_e32 v78, v78
	v_rcp_f32_e32 v79, v79
	v_pk_mul_f32 v[64:65], v[64:65], v[170:171] op_sel_hi:[1,0]
	v_pk_mul_f32 v[72:73], v[72:73], v[76:77]
	v_pk_mul_f32 v[60:61], v[60:61], v[166:167] op_sel_hi:[1,0]
	v_pk_mul_f32 v[72:73], v[64:65], v[72:73]
	v_pk_mul_f32 v[64:65], v[66:67], v[170:171] op_sel_hi:[1,0]
	v_pk_mul_f32 v[66:67], v[74:75], v[78:79]
	v_pk_mul_f32 v[62:63], v[62:63], v[166:167] op_sel_hi:[1,0]
	v_pk_mul_f32 v[74:75], v[64:65], v[66:67]
	v_cvt_pk_bf16_f32 v64, v68, v69
	v_mad_i64_i32 v[68:69], s[0:1], v156, s59, v[112:113]
	v_cvt_pk_bf16_f32 v65, v70, v71
	v_cvt_pk_bf16_f32 v66, v72, v73
	v_cvt_pk_bf16_f32 v67, v74, v75
	v_lshl_add_u64 v[68:69], v[68:69], 0, v[114:115]
	v_mul_f32_e32 v70, 0xbfb8aa3b, v60
	global_store_dwordx4 v[68:69], v[64:67], off
	s_waitcnt vmcnt(4)
	v_xor_b32_e32 v184, 16, v177
	v_xor_b32_e32 v185, 32, v177
	v_lshlrev_b32_e32 v184, 2, v184
	v_lshlrev_b32_e32 v185, 2, v185
	v_mov_b32_e32 v190, s10
	v_pk_add_f32 v[216:217], v[216:217], v[218:219]
	v_pk_add_f32 v[220:221], v[220:221], v[222:223]
	v_pk_add_f32 v[224:225], v[224:225], v[226:227]
	v_pk_add_f32 v[196:197], v[196:197], v[198:199]
	v_pk_add_f32 v[200:201], v[200:201], v[202:203]
	v_pk_add_f32 v[204:205], v[204:205], v[206:207]
	v_pk_add_f32 v[208:209], v[208:209], v[210:211]
	v_pk_add_f32 v[212:213], v[212:213], v[214:215]
	v_add_f32_e32 v216, v216, v217
	v_add_f32_e32 v220, v220, v221
	v_add_f32_e32 v224, v224, v225
	v_add_f32_e32 v196, v196, v197
	v_add_f32_e32 v200, v200, v201
	v_add_f32_e32 v204, v204, v205
	v_add_f32_e32 v208, v208, v209
	v_add_f32_e32 v212, v212, v213
	ds_bpermute_b32 v218, v184, v216
	ds_bpermute_b32 v219, v184, v220
	ds_bpermute_b32 v222, v184, v224
	ds_bpermute_b32 v223, v184, v196
	ds_bpermute_b32 v226, v184, v200
	ds_bpermute_b32 v227, v184, v204
	ds_bpermute_b32 v198, v184, v208
	ds_bpermute_b32 v199, v184, v212
	s_waitcnt lgkmcnt(0)
	v_add_f32_e32 v216, v216, v218
	v_add_f32_e32 v220, v220, v219
	v_add_f32_e32 v224, v224, v222
	v_add_f32_e32 v196, v196, v223
	v_add_f32_e32 v200, v200, v226
	v_add_f32_e32 v204, v204, v227
	v_add_f32_e32 v208, v208, v198
	v_add_f32_e32 v212, v212, v199
	ds_bpermute_b32 v218, v185, v216
	ds_bpermute_b32 v219, v185, v220
	ds_bpermute_b32 v222, v185, v224
	ds_bpermute_b32 v223, v185, v196
	ds_bpermute_b32 v226, v185, v200
	ds_bpermute_b32 v227, v185, v204
	ds_bpermute_b32 v198, v185, v208
	ds_bpermute_b32 v199, v185, v212
	s_waitcnt lgkmcnt(0)
	v_add_f32_e32 v216, v216, v218
	v_add_f32_e32 v220, v220, v219
	v_add_f32_e32 v224, v224, v222
	v_add_f32_e32 v196, v196, v223
	v_add_f32_e32 v200, v200, v226
	v_add_f32_e32 v204, v204, v227
	v_add_f32_e32 v208, v208, v198
	v_add_f32_e32 v212, v212, v199
	v_fma_f32 v216, v216, s8, v190
	v_fma_f32 v220, v220, s8, v190
	v_fma_f32 v224, v224, s8, v190
	v_fma_f32 v196, v196, s8, v190
	v_fma_f32 v200, v200, s8, v190
	v_fma_f32 v204, v204, s8, v190
	v_fma_f32 v208, v208, s8, v190
	v_fma_f32 v212, v212, s8, v190
	v_rsq_f32_e32 v240, v216
	v_rsq_f32_e32 v229, v220
	v_rsq_f32_e32 v230, v224
	v_rsq_f32_e32 v231, v196
	v_rsq_f32_e32 v232, v200
	v_rsq_f32_e32 v233, v204
	v_rsq_f32_e32 v234, v208
	v_rsq_f32_e32 v241, v212
	v_exp_f32_e32 v70, v70
	v_pk_mul_f32 v[52:53], v[52:53], v[166:167] op_sel_hi:[1,0]
	v_mul_f32_e32 v64, 0xbfb8aa3b, v61
	v_exp_f32_e32 v65, v64
	v_mul_f32_e32 v66, 0xbfb8aa3b, v62
	v_mul_f32_e32 v67, 0xbfb8aa3b, v63
	v_exp_f32_e32 v66, v66
	v_exp_f32_e32 v67, v67
	v_add_f32_e32 v64, 1.0, v70
	v_add_f32_e32 v65, 1.0, v65
	v_rcp_f32_e32 v64, v64
	v_rcp_f32_e32 v65, v65
	v_add_f32_e32 v66, 1.0, v66
	v_add_f32_e32 v67, 1.0, v67
	v_rcp_f32_e32 v66, v66
	v_rcp_f32_e32 v67, v67
	v_pk_mul_f32 v[60:61], v[60:61], v[64:65]
	v_pk_mul_f32 v[56:57], v[56:57], v[166:167] op_sel_hi:[1,0]
	v_pk_mul_f32 v[52:53], v[52:53], v[60:61]
	v_pk_mul_f32 v[60:61], v[62:63], v[66:67]
	v_mul_f32_e32 v62, 0xbfb8aa3b, v56
	v_exp_f32_e32 v62, v62
	v_pk_mul_f32 v[54:55], v[54:55], v[166:167] op_sel_hi:[1,0]
	v_pk_mul_f32 v[58:59], v[58:59], v[166:167] op_sel_hi:[1,0]
	v_pk_mul_f32 v[54:55], v[54:55], v[60:61]
	v_mul_f32_e32 v60, 0xbfb8aa3b, v57
	v_exp_f32_e32 v61, v60
	v_add_f32_e32 v60, 1.0, v62
	v_mul_f32_e32 v62, 0xbfb8aa3b, v58
	v_mul_f32_e32 v63, 0xbfb8aa3b, v59
	v_exp_f32_e32 v62, v62
	v_exp_f32_e32 v63, v63
	v_add_f32_e32 v61, 1.0, v61
	v_rcp_f32_e32 v60, v60
	v_rcp_f32_e32 v61, v61
	v_add_f32_e32 v62, 1.0, v62
	v_add_f32_e32 v63, 1.0, v63
	v_rcp_f32_e32 v62, v62
	v_rcp_f32_e32 v63, v63
	v_pk_mul_f32 v[48:49], v[48:49], v[166:167] op_sel_hi:[1,0]
	v_pk_mul_f32 v[56:57], v[56:57], v[60:61]
	v_pk_mul_f32 v[44:45], v[44:45], v[162:163] op_sel_hi:[1,0]
	v_pk_mul_f32 v[56:57], v[48:49], v[56:57]
	v_pk_mul_f32 v[48:49], v[50:51], v[166:167] op_sel_hi:[1,0]
	v_pk_mul_f32 v[50:51], v[58:59], v[62:63]
	v_pk_mul_f32 v[46:47], v[46:47], v[162:163] op_sel_hi:[1,0]
	v_pk_mul_f32 v[58:59], v[48:49], v[50:51]
	v_cvt_pk_bf16_f32 v48, v52, v53
	v_mad_i64_i32 v[52:53], s[0:1], v152, s59, v[112:113]
	v_cvt_pk_bf16_f32 v49, v54, v55
	v_cvt_pk_bf16_f32 v50, v56, v57
	v_cvt_pk_bf16_f32 v51, v58, v59
	v_lshl_add_u64 v[52:53], v[52:53], 0, v[114:115]
	v_mul_f32_e32 v54, 0xbfb8aa3b, v44
	global_store_dwordx4 v[52:53], v[48:51], off
	v_exp_f32_e32 v54, v54
	v_pk_mul_f32 v[36:37], v[36:37], v[162:163] op_sel_hi:[1,0]
	v_mul_f32_e32 v48, 0xbfb8aa3b, v45
	v_exp_f32_e32 v49, v48
	v_mul_f32_e32 v50, 0xbfb8aa3b, v46
	v_mul_f32_e32 v51, 0xbfb8aa3b, v47
	v_exp_f32_e32 v50, v50
	v_exp_f32_e32 v51, v51
	v_add_f32_e32 v48, 1.0, v54
	v_add_f32_e32 v49, 1.0, v49
	v_rcp_f32_e32 v48, v48
	v_rcp_f32_e32 v49, v49
	v_add_f32_e32 v50, 1.0, v50
	v_add_f32_e32 v51, 1.0, v51
	v_rcp_f32_e32 v50, v50
	v_rcp_f32_e32 v51, v51
	v_pk_mul_f32 v[44:45], v[44:45], v[48:49]
	v_pk_mul_f32 v[40:41], v[40:41], v[162:163] op_sel_hi:[1,0]
	v_pk_mul_f32 v[36:37], v[36:37], v[44:45]
	v_pk_mul_f32 v[44:45], v[46:47], v[50:51]
	v_mul_f32_e32 v46, 0xbfb8aa3b, v40
	v_exp_f32_e32 v46, v46
	v_pk_mul_f32 v[38:39], v[38:39], v[162:163] op_sel_hi:[1,0]
	v_pk_mul_f32 v[42:43], v[42:43], v[162:163] op_sel_hi:[1,0]
	v_pk_mul_f32 v[38:39], v[38:39], v[44:45]
	v_mul_f32_e32 v44, 0xbfb8aa3b, v41
	v_exp_f32_e32 v45, v44
	v_add_f32_e32 v44, 1.0, v46
	v_mul_f32_e32 v46, 0xbfb8aa3b, v42
	v_mul_f32_e32 v47, 0xbfb8aa3b, v43
	v_exp_f32_e32 v46, v46
	v_exp_f32_e32 v47, v47
	v_add_f32_e32 v45, 1.0, v45
	v_rcp_f32_e32 v44, v44
	v_rcp_f32_e32 v45, v45
	v_add_f32_e32 v46, 1.0, v46
	v_add_f32_e32 v47, 1.0, v47
	v_rcp_f32_e32 v46, v46
	v_rcp_f32_e32 v47, v47
	v_pk_mul_f32 v[32:33], v[32:33], v[162:163] op_sel_hi:[1,0]
	v_pk_mul_f32 v[40:41], v[40:41], v[44:45]
	v_pk_mul_f32 v[28:29], v[28:29], v[158:159] op_sel_hi:[1,0]
	v_pk_mul_f32 v[40:41], v[32:33], v[40:41]
	v_pk_mul_f32 v[32:33], v[34:35], v[162:163] op_sel_hi:[1,0]
	v_pk_mul_f32 v[34:35], v[42:43], v[46:47]
	v_pk_mul_f32 v[30:31], v[30:31], v[158:159] op_sel_hi:[1,0]
	v_pk_mul_f32 v[42:43], v[32:33], v[34:35]
	v_cvt_pk_bf16_f32 v32, v36, v37
	v_mad_i64_i32 v[36:37], s[0:1], v150, s59, v[112:113]
	v_cvt_pk_bf16_f32 v33, v38, v39
	v_cvt_pk_bf16_f32 v34, v40, v41
	v_cvt_pk_bf16_f32 v35, v42, v43
	v_lshl_add_u64 v[36:37], v[36:37], 0, v[114:115]
	v_mul_f32_e32 v38, 0xbfb8aa3b, v28
	global_store_dwordx4 v[36:37], v[32:35], off
	v_exp_f32_e32 v38, v38
	v_pk_mul_f32 v[20:21], v[20:21], v[158:159] op_sel_hi:[1,0]
	v_mul_f32_e32 v32, 0xbfb8aa3b, v29
	v_exp_f32_e32 v33, v32
	v_mul_f32_e32 v34, 0xbfb8aa3b, v30
	v_mul_f32_e32 v35, 0xbfb8aa3b, v31
	v_exp_f32_e32 v34, v34
	v_exp_f32_e32 v35, v35
	v_add_f32_e32 v32, 1.0, v38
	v_add_f32_e32 v33, 1.0, v33
	v_rcp_f32_e32 v32, v32
	v_rcp_f32_e32 v33, v33
	v_add_f32_e32 v34, 1.0, v34
	v_add_f32_e32 v35, 1.0, v35
	v_rcp_f32_e32 v34, v34
	v_rcp_f32_e32 v35, v35
	v_pk_mul_f32 v[28:29], v[28:29], v[32:33]
	v_pk_mul_f32 v[24:25], v[24:25], v[158:159] op_sel_hi:[1,0]
	v_pk_mul_f32 v[20:21], v[20:21], v[28:29]
	v_pk_mul_f32 v[28:29], v[30:31], v[34:35]
	v_mul_f32_e32 v30, 0xbfb8aa3b, v24
	v_exp_f32_e32 v30, v30
	v_pk_mul_f32 v[22:23], v[22:23], v[158:159] op_sel_hi:[1,0]
	v_pk_mul_f32 v[26:27], v[26:27], v[158:159] op_sel_hi:[1,0]
	v_pk_mul_f32 v[22:23], v[22:23], v[28:29]
	v_mul_f32_e32 v28, 0xbfb8aa3b, v25
	v_exp_f32_e32 v29, v28
	v_add_f32_e32 v28, 1.0, v30
	v_mul_f32_e32 v30, 0xbfb8aa3b, v26
	v_mul_f32_e32 v31, 0xbfb8aa3b, v27
	v_exp_f32_e32 v30, v30
	v_exp_f32_e32 v31, v31
	v_add_f32_e32 v29, 1.0, v29
	v_rcp_f32_e32 v28, v28
	v_rcp_f32_e32 v29, v29
	v_add_f32_e32 v30, 1.0, v30
	v_add_f32_e32 v31, 1.0, v31
	v_rcp_f32_e32 v30, v30
	v_rcp_f32_e32 v31, v31
	v_pk_mul_f32 v[16:17], v[16:17], v[158:159] op_sel_hi:[1,0]
	v_pk_mul_f32 v[24:25], v[24:25], v[28:29]
	v_pk_mul_f32 v[12:13], v[12:13], v[154:155] op_sel_hi:[1,0]
	v_pk_mul_f32 v[24:25], v[16:17], v[24:25]
	v_pk_mul_f32 v[16:17], v[18:19], v[158:159] op_sel_hi:[1,0]
	v_pk_mul_f32 v[18:19], v[26:27], v[30:31]
	v_pk_mul_f32 v[14:15], v[14:15], v[154:155] op_sel_hi:[1,0]
	v_pk_mul_f32 v[26:27], v[16:17], v[18:19]
	v_cvt_pk_bf16_f32 v16, v20, v21
	v_mad_i64_i32 v[20:21], s[0:1], v148, s59, v[112:113]
	v_cvt_pk_bf16_f32 v17, v22, v23
	v_cvt_pk_bf16_f32 v18, v24, v25
	v_cvt_pk_bf16_f32 v19, v26, v27
	v_lshl_add_u64 v[20:21], v[20:21], 0, v[114:115]
	v_mul_f32_e32 v22, 0xbfb8aa3b, v12
	global_store_dwordx4 v[20:21], v[16:19], off
	v_exp_f32_e32 v22, v22
	v_pk_mul_f32 v[4:5], v[4:5], v[154:155] op_sel_hi:[1,0]
	v_mul_f32_e32 v16, 0xbfb8aa3b, v13
	v_exp_f32_e32 v17, v16
	v_mul_f32_e32 v18, 0xbfb8aa3b, v14
	v_mul_f32_e32 v19, 0xbfb8aa3b, v15
	v_exp_f32_e32 v18, v18
	v_exp_f32_e32 v19, v19
	v_add_f32_e32 v16, 1.0, v22
	v_add_f32_e32 v17, 1.0, v17
	v_rcp_f32_e32 v16, v16
	v_rcp_f32_e32 v17, v17
	v_add_f32_e32 v18, 1.0, v18
	v_add_f32_e32 v19, 1.0, v19
	v_rcp_f32_e32 v18, v18
	v_rcp_f32_e32 v19, v19
	v_pk_mul_f32 v[12:13], v[12:13], v[16:17]
	v_pk_mul_f32 v[8:9], v[8:9], v[154:155] op_sel_hi:[1,0]
	v_pk_mul_f32 v[4:5], v[4:5], v[12:13]
	v_pk_mul_f32 v[12:13], v[14:15], v[18:19]
	v_mul_f32_e32 v14, 0xbfb8aa3b, v8
	v_exp_f32_e32 v14, v14
	v_pk_mul_f32 v[6:7], v[6:7], v[154:155] op_sel_hi:[1,0]
	v_pk_mul_f32 v[10:11], v[10:11], v[154:155] op_sel_hi:[1,0]
	v_pk_mul_f32 v[6:7], v[6:7], v[12:13]
	v_mul_f32_e32 v12, 0xbfb8aa3b, v9
	v_exp_f32_e32 v13, v12
	v_add_f32_e32 v12, 1.0, v14
	v_mul_f32_e32 v14, 0xbfb8aa3b, v10
	v_mul_f32_e32 v15, 0xbfb8aa3b, v11
	v_exp_f32_e32 v14, v14
	v_exp_f32_e32 v15, v15
	v_add_f32_e32 v13, 1.0, v13
	v_rcp_f32_e32 v12, v12
	v_rcp_f32_e32 v13, v13
	v_add_f32_e32 v14, 1.0, v14
	v_add_f32_e32 v15, 1.0, v15
	v_rcp_f32_e32 v14, v14
	v_rcp_f32_e32 v15, v15
	v_pk_mul_f32 v[0:1], v[0:1], v[154:155] op_sel_hi:[1,0]
	v_pk_mul_f32 v[8:9], v[8:9], v[12:13]
	s_and_b64 vcc, exec, s[2:3]
	v_pk_mul_f32 v[8:9], v[0:1], v[8:9]
	v_pk_mul_f32 v[0:1], v[2:3], v[154:155] op_sel_hi:[1,0]
	v_pk_mul_f32 v[2:3], v[10:11], v[14:15]
	s_mov_b32 s5, s12
	v_pk_mul_f32 v[10:11], v[0:1], v[2:3]
	v_cvt_pk_bf16_f32 v0, v4, v5
	v_mad_i64_i32 v[4:5], s[0:1], v146, s59, v[112:113]
	v_cvt_pk_bf16_f32 v1, v6, v7
	v_cvt_pk_bf16_f32 v2, v8, v9
	v_cvt_pk_bf16_f32 v3, v10, v11
	v_lshl_add_u64 v[4:5], v[4:5], 0, v[114:115]
	s_mov_b32 s4, s36
	s_mov_b64 s[42:43], s[40:41]
	s_mov_b64 s[44:45], s[38:39]
	global_store_dwordx4 v[4:5], v[0:3], off
	v_mov_b32_e32 v176, v229
	v_mov_b32_e32 v174, v230
	v_mov_b32_e32 v170, v231
	v_mov_b32_e32 v166, v232
	v_mov_b32_e32 v162, v233
	v_mov_b32_e32 v158, v234
	s_and_b64 vcc, exec, s[2:3]
	s_mov_b32 s5, s12
	s_mov_b32 s4, s36
	s_cbranch_vccz .LBB0_1090
	s_waitcnt vmcnt(0)
	s_cmpk_gt_u32 s9, 0xff
	s_cbranch_scc1 .LBB0_1097
	s_barrier
